# MLA tile loop hand rewrite without the wave stagger: persistent -mrun splat, no score copies, K1 reads after 2 MFMAs, max3 chains, PV interleaved with exps
# speedup vs baseline: 1.0467x; 1.0070x over previous
.LBB0_763:
	s_or_b64 exec, exec, s[0:1]
	s_lshl_b32 s0, s97, 16
	v_readlane_b32 s1, v247, 30
	s_add_u32 s0, s1, s0
	v_readlane_b32 s1, v247, 31
	s_addc_u32 s1, s1, 0
	s_lshl_b32 s11, s12, 1
	s_add_u32 s0, s0, s11
	s_addc_u32 s1, s1, 0
	v_lshlrev_b32_e32 v2, 1, v146
	v_mov_b32_e32 v3, v17
	v_lshl_add_u64 v[2:3], s[0:1], 0, v[2:3]
	v_lshl_add_u64 v[2:3], v[2:3], 0, v[16:17]
	global_load_dwordx4 v[2:5], v[2:3], off
	v_add_u32_e32 v177, v213, v144
	ds_read_b128 v[34:37], v177
	ds_read_b128 v[38:41], v177 offset:32
	ds_read_b128 v[42:45], v177 offset:64
	ds_read_b128 v[46:49], v177 offset:96
	ds_read_b128 v[66:69], v177 offset:128
	ds_read_b128 v[70:73], v177 offset:160
	v_mov_b32_e32 v51, v50
	v_mov_b32_e32 v52, v50
	v_mov_b32_e32 v53, v50
	v_mov_b32_e32 v54, v50
	v_mov_b32_e32 v55, v50
	v_mov_b32_e32 v56, v50
	v_mov_b32_e32 v57, v50
	v_mov_b32_e32 v58, v50
	v_mov_b32_e32 v59, v50
	v_mov_b32_e32 v60, v50
	v_mov_b32_e32 v61, v50
	v_mov_b32_e32 v62, v50
	v_mov_b32_e32 v63, v50
	v_mov_b32_e32 v64, v50
	v_mov_b32_e32 v65, v50
	v_mov_b64_e32 v[18:19], v[50:51]
	v_mov_b64_e32 v[20:21], v[52:53]
	v_mov_b64_e32 v[22:23], v[54:55]
	v_mov_b64_e32 v[24:25], v[56:57]
	v_mov_b64_e32 v[26:27], v[58:59]
	v_mov_b64_e32 v[28:29], v[60:61]
	v_mov_b64_e32 v[30:31], v[62:63]
	v_mov_b64_e32 v[32:33], v[64:65]
	v_add_u32_e32 v51, v214, v210
	ds_read_b128 v[52:55], v51 offset:13312
	ds_read_b128 v[90:93], v51 offset:13344
	ds_read_b128 v[94:97], v51 offset:17920
	ds_read_b128 v[98:101], v51 offset:17952
	s_waitcnt lgkmcnt(9)
	v_mfma_f32_32x32x16_bf16 v[18:33], v[34:37], v[124:127], v[18:33]
	s_waitcnt lgkmcnt(8)
	v_mfma_f32_32x32x16_bf16 v[18:33], v[38:41], v[120:123], v[18:33]
	s_waitcnt lgkmcnt(7)
	v_mfma_f32_32x32x16_bf16 v[18:33], v[42:45], v[116:119], v[18:33]
	s_waitcnt lgkmcnt(6)
	v_mfma_f32_32x32x16_bf16 v[18:33], v[46:49], v[112:115], v[18:33]
	s_waitcnt lgkmcnt(5)
	v_mfma_f32_32x32x16_bf16 v[18:33], v[66:69], v[108:111], v[18:33]
	s_waitcnt lgkmcnt(4)
	v_mfma_f32_32x32x16_bf16 v[18:33], v[70:73], v[104:107], v[18:33]
	s_nop 11
	v_max_f32_e32 v10, v18, v18
	v_max_f32_e32 v10, 0xf149f2ca, v10
	v_max3_f32 v10, v10, v19, v20
	v_max3_f32 v10, v10, v21, v22
	v_max3_f32 v10, v10, v23, v24
	v_max3_f32 v10, v10, v25, s86
	v_mov_b32_e32 v12, v10
	v_mov_b32_e32 v13, v10
	s_nop 1
	v_permlane32_swap_b32_e32 v12, v13
	v_cndmask_b32_e64 v12, v12, v13, s[6:7]
	v_max_f32_e32 v12, v12, v12
	v_max_f32_e32 v10, v10, v12
	v_exp_f32_e64 v12, -v10
	v_sub_f32_e32 v13, v19, v10
	v_sub_f32_e32 v16, v20, v10
	v_sub_f32_e32 v19, v22, v10
	v_mul_f32_e32 v32, 0, v12
	v_sub_f32_e32 v12, v18, v10
	v_sub_f32_e32 v18, v21, v10
	v_sub_f32_e32 v20, v23, v10
	v_sub_f32_e32 v21, v24, v10
	v_sub_f32_e32 v22, v25, v10
	v_exp_f32_e32 v12, v12
	v_exp_f32_e32 v13, v13
	v_exp_f32_e32 v48, v16
	v_exp_f32_e32 v49, v18
	v_exp_f32_e32 v84, v19
	v_exp_f32_e32 v85, v20
	v_exp_f32_e32 v86, v21
	v_exp_f32_e32 v87, v22
	v_mov_b32_e32 v33, v32
	v_mov_b32_e32 v34, v32
	v_mov_b32_e32 v35, v32
	v_mov_b32_e32 v36, v32
	v_mov_b32_e32 v37, v32
	v_mov_b32_e32 v38, v32
	v_mov_b32_e32 v39, v32
	v_mov_b32_e32 v40, v32
	v_mov_b32_e32 v41, v32
	v_mov_b32_e32 v42, v32
	v_mov_b32_e32 v43, v32
	v_mov_b32_e32 v44, v32
	v_mov_b32_e32 v45, v32
	v_mov_b32_e32 v46, v32
	v_mov_b32_e32 v47, v32
	v_cvt_pk_bf16_f32 v18, v12, v13
	v_cvt_pk_bf16_f32 v19, v48, v49
	v_cvt_pk_bf16_f32 v20, v84, v85
	v_cvt_pk_bf16_f32 v21, v86, v87
	v_sub_f32_e32 v16, 0xf149f2ca, v10
	s_waitcnt vmcnt(1)
	ds_write_b128 v89, v[6:9] offset:22528
	s_waitcnt lgkmcnt(4)
	v_mfma_f32_32x32x16_bf16 v[68:83], v[52:55], v[18:21], v[32:47]
	v_mov_b64_e32 v[66:67], v[46:47]
	v_mov_b64_e32 v[64:65], v[44:45]
	v_mov_b64_e32 v[62:63], v[42:43]
	v_mov_b64_e32 v[60:61], v[40:41]
	v_mov_b64_e32 v[58:59], v[38:39]
	v_mov_b64_e32 v[56:57], v[36:37]
	v_mov_b64_e32 v[54:55], v[34:35]
	v_mov_b64_e32 v[52:53], v[32:33]
	v_exp_f32_e32 v34, v16
	s_waitcnt lgkmcnt(2)
	v_mfma_f32_32x32x16_bf16 v[52:67], v[94:97], v[18:21], v[52:67]
	v_cvt_pk_bf16_f32 v18, v34, v34
	v_mov_b32_e32 v19, v18
	v_mov_b32_e32 v20, v18
	v_mov_b32_e32 v21, v18
	s_nop 1
	v_mfma_f32_32x32x16_bf16 v[68:83], v[90:93], v[18:21], v[68:83]
	s_waitcnt lgkmcnt(1)
	v_mfma_f32_32x32x16_bf16 v[52:67], v[98:101], v[18:21], v[52:67]
	s_and_saveexec_b64 s[0:1], s[2:3]
	ds_write_b128 v11, v[128:131] offset:22656
	s_or_b64 exec, exec, s[0:1]
	v_pk_add_f32 v[6:7], v[12:13], 0 op_sel_hi:[1,0]
	s_bfe_u32 s25, s84, 0x4000b
	v_pk_add_f32 v[6:7], v[48:49], v[6:7]
	v_mad_u64_u32 v[184:185], s[0:1], s25, v221, v[168:169]
	v_pk_add_f32 v[6:7], v[84:85], v[6:7]
	v_mov_b32_e32 v18, v17
	v_pk_add_f32 v[6:7], v[86:87], v[6:7]
	v_mov_b32_e32 v19, v17
	v_pk_add_f32 v[6:7], v[34:35], v[6:7] op_sel_hi:[0,1]
	v_pk_add_f32 v[6:7], v[34:35], v[6:7] op_sel_hi:[0,1]
	v_pk_add_f32 v[6:7], v[34:35], v[6:7] op_sel_hi:[0,1]
	v_pk_add_f32 v[6:7], v[34:35], v[6:7] op_sel_hi:[0,1]
	v_pk_add_f32 v[6:7], v[6:7], v[6:7] op_sel_hi:[0,1]
	v_mov_b32_e32 v20, v17
	v_mov_b32_e32 v21, v17
	v_mov_b32_e32 v22, v17
	v_mov_b32_e32 v23, v17
	v_mov_b32_e32 v24, v17
	v_mov_b32_e32 v25, v17
	v_mov_b32_e32 v26, v17
	v_mov_b32_e32 v27, v17
	v_mov_b32_e32 v28, v17
	v_mov_b32_e32 v29, v17
	v_mov_b32_e32 v30, v17
	v_mov_b32_e32 v31, v17
	v_mov_b32_e32 v11, v32
	v_mov_b32_e32 v6, v17
	s_lshl_b32 s30, s16, 3
	s_lshl_b32 s0, s25, 21
	s_lshl_b32 s1, s17, 7
	v_mov_b32_e32 v16, v17
	v_pk_add_f32 v[182:183], v[10:11], v[6:7]
	s_add_i32 s11, s24, s30
	s_or_b32 s0, s0, s1
	s_mov_b32 s1, s9
	v_add_u32_e32 v6, 0x8800, v88
	s_waitcnt vmcnt(0)
	v_mov_b64_e32 v[48:49], v[30:31]
	v_lshl_add_u64 v[186:187], v[170:171], 0, s[8:9]
	v_lshl_add_u64 v[188:189], v[172:173], 0, s[0:1]
	s_or_b32 s24, s30, 6
	s_add_i32 s25, s11, -1
	s_mov_b32 s48, 0
	s_mov_b32 s49, 2
	v_mov_b64_e32 v[46:47], v[28:29]
	v_mov_b64_e32 v[44:45], v[26:27]
	v_mov_b64_e32 v[42:43], v[24:25]
	v_mov_b64_e32 v[40:41], v[22:23]
	v_mov_b64_e32 v[38:39], v[20:21]
	v_mov_b64_e32 v[36:37], v[18:19]
	v_mov_b64_e32 v[34:35], v[16:17]
	ds_write2_b64 v6, v[2:3], v[4:5] offset0:128 offset1:130
	s_waitcnt lgkmcnt(0)
	s_barrier
	v_xor_b32_e32 v18, 0x80000000, v182
	v_mov_b32_e32 v19, v18
	v_mov_b32_e32 v20, v18
	v_mov_b32_e32 v21, v18
	v_mov_b32_e32 v22, v18
	v_mov_b32_e32 v23, v18
	v_mov_b32_e32 v24, v18
	v_mov_b32_e32 v25, v18
	v_mov_b32_e32 v26, v18
	v_mov_b32_e32 v27, v18
	v_mov_b32_e32 v28, v18
	v_mov_b32_e32 v29, v18
	v_mov_b32_e32 v30, v18
	v_mov_b32_e32 v31, v18
	v_mov_b32_e32 v32, v18
	v_mov_b32_e32 v33, v18
	global_load_dwordx4 v[136:139], v[188:189], off
	s_and_saveexec_b64 s[0:1], s[2:3]
	s_cbranch_execz .LBB0_767

.LBB0_767:
	s_or_b64 exec, exec, s[0:1]
	global_load_dwordx4 v[132:135], v[186:187], off
	s_cmp_gt_u32 s48, s11
	s_cbranch_scc1 .LBB0_790
	s_bitcmp1_b32 s49, 0
	s_cselect_b32 s0, 0, 0x5800
	v_add_u32_e32 v16, s0, v211
	v_add_u32_e32 v16, v16, v144
	ds_read_b128 v[190:193], v16
	ds_read_b128 v[194:197], v16 offset:32
	ds_read_b128 v[222:225], v16 offset:64
	ds_read_b128 v[226:229], v16 offset:96
	ds_read_b128 v[230:233], v16 offset:128
	ds_read_b128 v[234:237], v16 offset:160
	s_cmp_lt_u32 s48, s11
	s_cselect_b64 s[30:31], -1, 0
	s_andn2_b64 s[80:81], exec, s[30:31]
	s_cmp_lt_u32 s48, s11
	s_cbranch_scc0 .Lmla_c1only
	s_waitcnt lgkmcnt(5)
	v_mfma_f32_32x32x16_bf16 v[84:99], v[190:193], v[124:127], v[18:33]
	s_waitcnt lgkmcnt(4)
	v_mfma_f32_32x32x16_bf16 v[84:99], v[194:197], v[120:123], v[84:99]
	ds_read_b128 v[238:241], v16 offset:6656
	ds_read_b128 v[242:245], v16 offset:6688
	ds_read_b128 v[248:251], v16 offset:6720
	ds_read_b128 v[252:255], v16 offset:6752
	ds_read_b128 v[2:5], v16 offset:6784
	ds_read_b128 v[6:9], v16 offset:6816
	s_waitcnt lgkmcnt(9)
	v_mfma_f32_32x32x16_bf16 v[84:99], v[222:225], v[116:119], v[84:99]
	s_waitcnt lgkmcnt(8)
	v_mfma_f32_32x32x16_bf16 v[84:99], v[226:229], v[112:115], v[84:99]
	s_waitcnt lgkmcnt(7)
	v_mfma_f32_32x32x16_bf16 v[84:99], v[230:233], v[108:111], v[84:99]
	s_waitcnt lgkmcnt(6)
	v_mfma_f32_32x32x16_bf16 v[84:99], v[234:237], v[104:107], v[84:99]
	s_waitcnt lgkmcnt(5)
	v_mfma_f32_32x32x16_bf16 v[34:49], v[238:241], v[124:127], v[18:33]
	s_waitcnt lgkmcnt(4)
	v_mfma_f32_32x32x16_bf16 v[34:49], v[242:245], v[120:123], v[34:49]
	s_waitcnt lgkmcnt(3)
	v_mfma_f32_32x32x16_bf16 v[34:49], v[248:251], v[116:119], v[34:49]
	s_waitcnt lgkmcnt(2)
	v_mfma_f32_32x32x16_bf16 v[34:49], v[252:255], v[112:115], v[34:49]
	s_waitcnt lgkmcnt(1)
	v_mfma_f32_32x32x16_bf16 v[34:49], v[2:5], v[108:111], v[34:49]
	s_waitcnt lgkmcnt(0)
	v_mfma_f32_32x32x16_bf16 v[34:49], v[6:9], v[104:107], v[34:49]
	v_max3_i32 v16, v84, v85, v86
	v_max3_i32 v16, v16, v87, v88
	v_max3_i32 v16, v16, v89, v90
	v_max3_i32 v16, v16, v91, v92
	v_max3_i32 v16, v16, v93, v94
	v_max3_i32 v16, v16, v95, v96
	v_max3_i32 v16, v16, v97, v98
	v_max_i32_e32 v16, v16, v99
	v_add_u32_e32 v239, s0, v144
	v_add_u32_e32 v239, v239, v210
	ds_read_b128 v[190:193], v239 offset:13312
	ds_read_b128 v[194:197], v239 offset:13344
	ds_read_b128 v[222:225], v239 offset:17920
	ds_read_b128 v[226:229], v239 offset:17952
	ds_read_b128 v[10:13], v239 offset:13376
	ds_read_b128 v[230:233], v239 offset:13408
	ds_read_b128 v[100:103], v239 offset:17984
	ds_read_b128 v[234:237], v239 offset:18016
	s_cmp_lg_u32 s25, s48
	s_cbranch_scc1 .Lmla_nomask1
	v_add_u32_e32 v239, v215, v216
	v_cmp_lt_i32_e32 vcc, -1, v239
	s_nop 1
	v_cndmask_b32_e32 v34, v218, v34, vcc
	v_cmp_lt_i32_e32 vcc, 0, v239
	s_nop 1
	v_cndmask_b32_e32 v35, v218, v35, vcc
	v_cmp_lt_i32_e32 vcc, 1, v239
	s_nop 1
	v_cndmask_b32_e32 v36, v218, v36, vcc
	v_cmp_lt_i32_e32 vcc, 2, v239
	s_nop 1
	v_cndmask_b32_e32 v37, v218, v37, vcc
	v_cmp_lt_i32_e32 vcc, 7, v239
	s_nop 1
	v_cndmask_b32_e32 v38, v218, v38, vcc
	v_cmp_lt_i32_e32 vcc, 8, v239
	s_nop 1
	v_cndmask_b32_e32 v39, v218, v39, vcc
	v_cmp_lt_i32_e32 vcc, 9, v239
	s_nop 1
	v_cndmask_b32_e32 v40, v218, v40, vcc
	v_cmp_lt_i32_e32 vcc, 10, v239
	s_nop 1
	v_cndmask_b32_e32 v41, v218, v41, vcc
	v_cmp_lt_i32_e32 vcc, 15, v239
	s_nop 1
	v_cndmask_b32_e32 v42, v218, v42, vcc
	v_cmp_lt_i32_e32 vcc, 16, v239
	s_nop 1
	v_cndmask_b32_e32 v43, v218, v43, vcc
	v_cmp_lt_i32_e32 vcc, 17, v239
	s_nop 1
	v_cndmask_b32_e32 v44, v218, v44, vcc
	v_cmp_lt_i32_e32 vcc, 18, v239
	s_nop 1
	v_cndmask_b32_e32 v45, v218, v45, vcc
	v_cmp_lt_i32_e32 vcc, 23, v239
	s_nop 1
	v_cndmask_b32_e32 v46, v218, v46, vcc
	v_cmp_lt_i32_e32 vcc, 24, v239
	s_nop 1
	v_cndmask_b32_e32 v47, v218, v47, vcc
	v_cmp_lt_i32_e32 vcc, 25, v239
	s_nop 1
	v_cndmask_b32_e32 v48, v218, v48, vcc
	v_cmp_lt_i32_e32 vcc, 26, v239
	s_nop 1
	v_cndmask_b32_e32 v49, v218, v49, vcc
.Lmla_nomask1:
	v_max3_i32 v238, v34, v35, v36
	v_max3_i32 v238, v238, v37, v38
	v_max3_i32 v238, v238, v39, v40
	v_max3_i32 v238, v238, v41, v42
	v_max3_i32 v238, v238, v43, v44
	v_max3_i32 v238, v238, v45, v46
	v_max3_i32 v238, v238, v47, v48
	v_max_i32_e32 v238, v238, v49
	v_max_i32_e32 v16, v16, v238
	s_branch .LBB0_778
.Lmla_c1only:
	s_waitcnt lgkmcnt(5)
	v_mfma_f32_32x32x16_bf16 v[84:99], v[190:193], v[124:127], v[18:33]
	s_waitcnt lgkmcnt(4)
	v_mfma_f32_32x32x16_bf16 v[84:99], v[194:197], v[120:123], v[84:99]
	s_waitcnt lgkmcnt(3)
	v_mfma_f32_32x32x16_bf16 v[84:99], v[222:225], v[116:119], v[84:99]
	s_waitcnt lgkmcnt(2)
	v_mfma_f32_32x32x16_bf16 v[84:99], v[226:229], v[112:115], v[84:99]
	s_waitcnt lgkmcnt(1)
	v_mfma_f32_32x32x16_bf16 v[84:99], v[230:233], v[108:111], v[84:99]
	s_waitcnt lgkmcnt(0)
	v_mfma_f32_32x32x16_bf16 v[84:99], v[234:237], v[104:107], v[84:99]
	s_nop 7
	v_add_u32_e32 v16, s0, v144
	v_add_u32_e32 v16, v16, v210
	ds_read_b128 v[190:193], v16 offset:13312
	ds_read_b128 v[194:197], v16 offset:13344
	ds_read_b128 v[222:225], v16 offset:17920
	ds_read_b128 v[226:229], v16 offset:17952
	s_cmp_eq_u32 s11, s48
	s_cbranch_scc0 .Lmla_nomask0
	v_add_u32_e32 v16, v215, v216
	v_cmp_lt_i32_e32 vcc, -1, v16
	s_nop 1
	v_cndmask_b32_e32 v84, v218, v84, vcc
	v_cmp_lt_i32_e32 vcc, 0, v16
	s_nop 1
	v_cndmask_b32_e32 v85, v218, v85, vcc
	v_cmp_lt_i32_e32 vcc, 1, v16
	s_nop 1
	v_cndmask_b32_e32 v86, v218, v86, vcc
	v_cmp_lt_i32_e32 vcc, 2, v16
	s_nop 1
	v_cndmask_b32_e32 v87, v218, v87, vcc
	v_cmp_lt_i32_e32 vcc, 7, v16
	s_nop 1
	v_cndmask_b32_e32 v88, v218, v88, vcc
	v_cmp_lt_i32_e32 vcc, 8, v16
	s_nop 1
	v_cndmask_b32_e32 v89, v218, v89, vcc
	v_cmp_lt_i32_e32 vcc, 9, v16
	s_nop 1
	v_cndmask_b32_e32 v90, v218, v90, vcc
	v_cmp_lt_i32_e32 vcc, 10, v16
	s_nop 1
	v_cndmask_b32_e32 v91, v218, v91, vcc
	v_cmp_lt_i32_e32 vcc, 15, v16
	s_nop 1
	v_cndmask_b32_e32 v92, v218, v92, vcc
	v_cmp_lt_i32_e32 vcc, 16, v16
	s_nop 1
	v_cndmask_b32_e32 v93, v218, v93, vcc
	v_cmp_lt_i32_e32 vcc, 17, v16
	s_nop 1
	v_cndmask_b32_e32 v94, v218, v94, vcc
	v_cmp_lt_i32_e32 vcc, 18, v16
	s_nop 1
	v_cndmask_b32_e32 v95, v218, v95, vcc
	v_cmp_lt_i32_e32 vcc, 23, v16
	s_nop 1
	v_cndmask_b32_e32 v96, v218, v96, vcc
	v_cmp_lt_i32_e32 vcc, 24, v16
	s_nop 1
	v_cndmask_b32_e32 v97, v218, v97, vcc
	v_cmp_lt_i32_e32 vcc, 25, v16
	s_nop 1
	v_cndmask_b32_e32 v98, v218, v98, vcc
	v_cmp_lt_i32_e32 vcc, 26, v16
	s_nop 1
	v_cndmask_b32_e32 v99, v218, v99, vcc
.Lmla_nomask0:
	v_max3_i32 v16, v84, v85, v86
	v_max3_i32 v16, v16, v87, v88
	v_max3_i32 v16, v16, v89, v90
	v_max3_i32 v16, v16, v91, v92
	v_max3_i32 v16, v16, v93, v94
	v_max3_i32 v16, v16, v95, v96
	v_max3_i32 v16, v16, v97, v98
	v_max_i32_e32 v16, v16, v99
.LBB0_778:
	v_cmp_lt_f32_e32 vcc, s47, v16
	s_cbranch_vccz .LBB0_785
	v_max3_f32 v16, v84, s86, v85
	v_max3_f32 v16, v16, v86, v87
	v_max3_f32 v16, v16, v88, v89
	v_max3_f32 v16, v16, v90, v91
	v_max3_f32 v16, v16, v92, v93
	v_max3_f32 v16, v16, v94, v95
	v_max3_f32 v16, v16, v96, v97
	s_and_b64 vcc, exec, s[80:81]
	v_max3_f32 v16, v16, v98, v99
	s_cbranch_vccnz .LBB0_781
	v_max3_f32 v16, v16, v34, v35
	v_max3_f32 v16, v16, v36, v37
	v_max3_f32 v16, v16, v38, v39
	v_max3_f32 v16, v16, v40, v41
	v_max3_f32 v16, v16, v42, v43
	v_max3_f32 v16, v16, v44, v45
	v_max3_f32 v16, v16, v46, v47
	v_max3_f32 v16, v16, v48, v49
.LBB0_781:
	v_mov_b32_e32 v238, v16
	v_mov_b32_e32 v239, v16
	s_nop 1
	v_permlane32_swap_b32_e32 v238, v239
	v_cndmask_b32_e64 v238, v238, v239, s[6:7]
	s_and_b64 vcc, exec, s[80:81]
	v_max3_f32 v16, v16, v238, 0
	s_cbranch_vccnz .LBB0_783
	v_sub_f32_e32 v49, v49, v16
	v_sub_f32_e32 v48, v48, v16
	v_sub_f32_e32 v47, v47, v16
	v_sub_f32_e32 v46, v46, v16
	v_sub_f32_e32 v45, v45, v16
	v_sub_f32_e32 v44, v44, v16
	v_sub_f32_e32 v43, v43, v16
	v_sub_f32_e32 v42, v42, v16
	v_sub_f32_e32 v41, v41, v16
	v_sub_f32_e32 v40, v40, v16
	v_sub_f32_e32 v39, v39, v16
	v_sub_f32_e32 v38, v38, v16
	v_sub_f32_e32 v37, v37, v16
	v_sub_f32_e32 v36, v36, v16
	v_sub_f32_e32 v35, v35, v16
	v_sub_f32_e32 v34, v34, v16
	v_sub_f32_e32 v99, v99, v16
	v_sub_f32_e32 v98, v98, v16
	v_sub_f32_e32 v97, v97, v16
	v_sub_f32_e32 v96, v96, v16
	v_sub_f32_e32 v95, v95, v16
	v_sub_f32_e32 v94, v94, v16
	v_sub_f32_e32 v93, v93, v16
	v_sub_f32_e32 v92, v92, v16
	v_sub_f32_e32 v91, v91, v16
	v_sub_f32_e32 v90, v90, v16
	v_sub_f32_e32 v89, v89, v16
	v_sub_f32_e32 v88, v88, v16
	v_sub_f32_e32 v87, v87, v16
	v_sub_f32_e32 v86, v86, v16
	s_branch .LBB0_784
.LBB0_783:
	v_pk_add_f32 v[86:87], v[86:87], v[16:17] op_sel_hi:[1,0] neg_lo:[0,1] neg_hi:[0,1]
	v_pk_add_f32 v[88:89], v[88:89], v[16:17] op_sel_hi:[1,0] neg_lo:[0,1] neg_hi:[0,1]
	v_pk_add_f32 v[90:91], v[90:91], v[16:17] op_sel_hi:[1,0] neg_lo:[0,1] neg_hi:[0,1]
	v_pk_add_f32 v[92:93], v[92:93], v[16:17] op_sel_hi:[1,0] neg_lo:[0,1] neg_hi:[0,1]
	v_pk_add_f32 v[94:95], v[94:95], v[16:17] op_sel_hi:[1,0] neg_lo:[0,1] neg_hi:[0,1]
	v_pk_add_f32 v[96:97], v[96:97], v[16:17] op_sel_hi:[1,0] neg_lo:[0,1] neg_hi:[0,1]
	v_pk_add_f32 v[98:99], v[98:99], v[16:17] op_sel_hi:[1,0] neg_lo:[0,1] neg_hi:[0,1]
.LBB0_784:
	v_exp_f32_e64 v238, -v16
	v_sub_f32_e32 v85, v85, v16
	v_sub_f32_e32 v84, v84, v16
	v_add_f32_e32 v182, v182, v16
	v_mul_f32_e32 v183, v183, v238
	v_pk_mul_f32 v[82:83], v[82:83], v[238:239] op_sel_hi:[1,0]
	v_pk_mul_f32 v[80:81], v[80:81], v[238:239] op_sel_hi:[1,0]
	v_pk_mul_f32 v[78:79], v[78:79], v[238:239] op_sel_hi:[1,0]
	v_pk_mul_f32 v[76:77], v[76:77], v[238:239] op_sel_hi:[1,0]
	v_pk_mul_f32 v[74:75], v[74:75], v[238:239] op_sel_hi:[1,0]
	v_pk_mul_f32 v[72:73], v[72:73], v[238:239] op_sel_hi:[1,0]
	v_pk_mul_f32 v[70:71], v[70:71], v[238:239] op_sel_hi:[1,0]
	v_pk_mul_f32 v[68:69], v[68:69], v[238:239] op_sel_hi:[1,0]
	v_pk_mul_f32 v[66:67], v[66:67], v[238:239] op_sel_hi:[1,0]
	v_pk_mul_f32 v[64:65], v[64:65], v[238:239] op_sel_hi:[1,0]
	v_pk_mul_f32 v[62:63], v[62:63], v[238:239] op_sel_hi:[1,0]
	v_pk_mul_f32 v[60:61], v[60:61], v[238:239] op_sel_hi:[1,0]
	v_pk_mul_f32 v[58:59], v[58:59], v[238:239] op_sel_hi:[1,0]
	v_pk_mul_f32 v[56:57], v[56:57], v[238:239] op_sel_hi:[1,0]
	v_pk_mul_f32 v[54:55], v[54:55], v[238:239] op_sel_hi:[1,0]
	v_pk_mul_f32 v[52:53], v[52:53], v[238:239] op_sel_hi:[1,0]
	v_xor_b32_e32 v18, 0x80000000, v182
	v_mov_b32_e32 v19, v18
	v_mov_b32_e32 v20, v18
	v_mov_b32_e32 v21, v18
	v_mov_b32_e32 v22, v18
	v_mov_b32_e32 v23, v18
	v_mov_b32_e32 v24, v18
	v_mov_b32_e32 v25, v18
	v_mov_b32_e32 v26, v18
	v_mov_b32_e32 v27, v18
	v_mov_b32_e32 v28, v18
	v_mov_b32_e32 v29, v18
	v_mov_b32_e32 v30, v18
	v_mov_b32_e32 v31, v18
	v_mov_b32_e32 v32, v18
	v_mov_b32_e32 v33, v18
.LBB0_785:
	v_exp_f32_e32 v84, v84
	v_exp_f32_e32 v85, v85
	v_exp_f32_e32 v86, v86
	v_exp_f32_e32 v87, v87
	v_exp_f32_e32 v88, v88
	v_exp_f32_e32 v89, v89
	v_exp_f32_e32 v90, v90
	v_exp_f32_e32 v91, v91
	v_exp_f32_e32 v92, v92
	v_exp_f32_e32 v93, v93
	v_cvt_pk_bf16_f32 v240, v84, v85
	v_cvt_pk_bf16_f32 v241, v86, v87
	v_exp_f32_e32 v94, v94
	v_exp_f32_e32 v95, v95
	v_cvt_pk_bf16_f32 v242, v88, v89
	v_cvt_pk_bf16_f32 v243, v90, v91
	v_exp_f32_e32 v96, v96
	v_exp_f32_e32 v97, v97
	v_pk_add_f32 v[238:239], v[84:85], 0 op_sel_hi:[1,0]
	s_waitcnt lgkmcnt(0)
	v_mfma_f32_32x32x16_bf16 v[68:83], v[190:193], v[240:243], v[68:83]
	v_exp_f32_e32 v98, v98
	v_exp_f32_e32 v99, v99
	v_pk_add_f32 v[238:239], v[86:87], v[238:239]
	v_mfma_f32_32x32x16_bf16 v[52:67], v[222:225], v[240:243], v[52:67]
	v_cvt_pk_bf16_f32 v248, v92, v93
	v_cvt_pk_bf16_f32 v249, v94, v95
	v_cvt_pk_bf16_f32 v250, v96, v97
	v_pk_add_f32 v[238:239], v[88:89], v[238:239]
	v_cvt_pk_bf16_f32 v251, v98, v99
	v_pk_add_f32 v[238:239], v[90:91], v[238:239]
	v_pk_add_f32 v[238:239], v[92:93], v[238:239]
	v_mfma_f32_32x32x16_bf16 v[68:83], v[194:197], v[248:251], v[68:83]
	v_pk_add_f32 v[238:239], v[94:95], v[238:239]
	v_mfma_f32_32x32x16_bf16 v[52:67], v[226:229], v[248:251], v[52:67]
	v_pk_add_f32 v[238:239], v[96:97], v[238:239]
	v_pk_add_f32 v[238:239], v[98:99], v[238:239]
	s_and_b64 vcc, exec, s[80:81]
	s_cbranch_vccnz .LBB0_789
	v_exp_f32_e32 v34, v34
	v_exp_f32_e32 v35, v35
	v_exp_f32_e32 v36, v36
	v_exp_f32_e32 v37, v37
	v_exp_f32_e32 v38, v38
	v_exp_f32_e32 v39, v39
	v_exp_f32_e32 v40, v40
	v_exp_f32_e32 v41, v41
	v_cvt_pk_bf16_f32 v252, v34, v35
	v_cvt_pk_bf16_f32 v253, v36, v37
	v_exp_f32_e32 v42, v42
	v_exp_f32_e32 v43, v43
	v_cvt_pk_bf16_f32 v254, v38, v39
	v_cvt_pk_bf16_f32 v255, v40, v41
	v_exp_f32_e32 v44, v44
	v_exp_f32_e32 v45, v45
	v_pk_add_f32 v[238:239], v[34:35], v[238:239]
	v_mfma_f32_32x32x16_bf16 v[68:83], v[10:13], v[252:255], v[68:83]
	v_exp_f32_e32 v46, v46
	v_exp_f32_e32 v47, v47
	v_mfma_f32_32x32x16_bf16 v[52:67], v[100:103], v[252:255], v[52:67]
	v_exp_f32_e32 v48, v48
	v_exp_f32_e32 v49, v49
	v_pk_add_f32 v[238:239], v[36:37], v[238:239]
	v_cvt_pk_bf16_f32 v240, v42, v43
	v_cvt_pk_bf16_f32 v241, v44, v45
	v_cvt_pk_bf16_f32 v242, v46, v47
	v_pk_add_f32 v[238:239], v[38:39], v[238:239]
	v_cvt_pk_bf16_f32 v243, v48, v49
	v_pk_add_f32 v[238:239], v[40:41], v[238:239]
	v_pk_add_f32 v[238:239], v[42:43], v[238:239]
	v_mfma_f32_32x32x16_bf16 v[68:83], v[230:233], v[240:243], v[68:83]
	v_pk_add_f32 v[238:239], v[44:45], v[238:239]
	v_mfma_f32_32x32x16_bf16 v[52:67], v[234:237], v[240:243], v[52:67]
	v_pk_add_f32 v[238:239], v[46:47], v[238:239]
	v_pk_add_f32 v[238:239], v[48:49], v[238:239]
.LBB0_789:
	v_add_f32_e32 v16, v238, v239
	v_add_f32_e32 v183, v183, v16
